# all 8 compiler-inserted conservative vmcnt(0) around the GEMM prologues / unit headers removed (counted waits of the template remain)
# speedup vs baseline: 1.0060x; 1.0028x over previous
.LBB0_346:
	v_and_b32_e32 v187, 15, v184
	v_or_b32_e32 v14, s87, v187
	v_lshlrev_b32_e32 v15, 6, v14
	s_mov_b64 s[18:19], 0x80
	v_and_b32_e32 v15, 0x3c0, v15
	v_and_b32_e32 v186, 48, v184
	v_and_b32_e32 v17, 0xfffffc00, v185
	v_lshlrev_b32_e32 v14, 2, v14
	s_add_i32 m0, s44, 0x18000
	v_lshl_add_u64 v[6:7], v[6:7], 0, s[18:19]
	s_sext_i32_i8 s73, s6
	v_or_b32_e32 v16, v15, v186
	v_add_u32_e32 v18, s86, v17
	v_and_b32_e32 v14, 32, v14
	v_readlane_b32 s6, v250, 8
	s_waitcnt vmcnt(2)
	s_barrier
	global_load_lds_dwordx4 v[6:7], off
	v_lshl_add_u64 v[4:5], v[4:5], 0, s[18:19]
	s_add_i32 m0, s44, 0x1a000
	s_add_i32 s74, s44, 0x8000
	s_add_i32 s75, s44, 0xa000
	v_bitop3_b32 v188, v15, v14, v186 bitop3:0x36
	v_bitop3_b32 v14, v16, v18, v14 bitop3:0xde
	v_add_u32_e32 v16, s6, v17
	global_load_lds_dwordx4 v[4:5], off
	v_lshl_add_u64 v[0:1], v[0:1], 0, s[18:19]
	s_mov_b32 m0, s74
	s_add_u32 s6, s30, 0x160080
	global_load_lds_dwordx4 v[0:1], off
	v_lshl_add_u64 v[0:1], v[2:3], 0, s[18:19]
	s_mov_b32 m0, s75
	s_addc_u32 s7, s31, 0
	global_load_lds_dwordx4 v[0:1], off
	s_add_i32 m0, s44, 0x1c000
	v_lshl_add_u64 v[0:1], s[6:7], 0, v[170:171]
	global_load_lds_dwordx4 v[0:1], off
	v_lshl_add_u64 v[0:1], s[6:7], 0, v[174:175]
	s_add_i32 m0, s44, 0x1e000
	v_lshlrev_b32_e32 v17, 2, v184
	global_load_lds_dwordx4 v[0:1], off
	v_and_b32_e32 v0, 0xffff0, v8
	v_add_lshl_u32 v0, v9, v0, 12
	s_waitcnt vmcnt(6)
	v_lshl_add_u32 v162, v10, 1, v0
	v_and_b32_e32 v0, 0xffff0, v11
	v_lshl_or_b32 v15, v187, 6, v186
	v_and_b32_e32 v17, 32, v17
	s_cmpk_lt_u32 s33, 0x100
	v_add_lshl_u32 v0, v12, v0, 12
	v_bitop3_b32 v189, v15, v16, v17 bitop3:0xde
	s_cselect_b64 s[20:21], -1, 0
	v_lshl_add_u32 v164, v13, 1, v0
	v_mov_b32_e32 v163, v161
	v_mov_b32_e32 v165, v161
	v_mov_b64_e32 v[166:167], 0x100
	v_mov_b64_e32 v[168:169], 0xff
	v_add_u32_e32 v190, 0, v14
	v_mov_b32_e32 v0, v161
	v_mov_b32_e32 v1, v161
	v_mov_b32_e32 v2, v161
	v_mov_b32_e32 v3, v161
	v_mov_b32_e32 v4, v161
	v_mov_b32_e32 v5, v161
	v_mov_b32_e32 v6, v161
	v_mov_b32_e32 v7, v161
	v_mov_b32_e32 v16, v161
	v_mov_b32_e32 v17, v161
	v_mov_b32_e32 v18, v161
	v_mov_b32_e32 v19, v161
	v_mov_b32_e32 v20, v161
	v_mov_b32_e32 v21, v161
	v_mov_b32_e32 v22, v161
	v_mov_b32_e32 v23, v161
	v_mov_b32_e32 v32, v161
	v_mov_b32_e32 v33, v161
	v_mov_b32_e32 v34, v161
	v_mov_b32_e32 v35, v161
	v_mov_b32_e32 v36, v161
	v_mov_b32_e32 v37, v161
	v_mov_b32_e32 v38, v161
	v_mov_b32_e32 v39, v161
	v_mov_b32_e32 v48, v161
	v_mov_b32_e32 v49, v161
	v_mov_b32_e32 v50, v161
	v_mov_b32_e32 v51, v161
	v_mov_b32_e32 v52, v161
	v_mov_b32_e32 v53, v161
	v_mov_b32_e32 v54, v161
	v_mov_b32_e32 v55, v161
	v_mov_b32_e32 v8, v161
	v_mov_b32_e32 v9, v161
	v_mov_b32_e32 v10, v161
	v_mov_b32_e32 v11, v161
	v_mov_b32_e32 v12, v161
	v_mov_b32_e32 v13, v161
	v_mov_b32_e32 v14, v161
	v_mov_b32_e32 v15, v161
	v_mov_b32_e32 v24, v161
	v_mov_b32_e32 v25, v161
	v_mov_b32_e32 v26, v161
	v_mov_b32_e32 v27, v161
	v_mov_b32_e32 v28, v161
	v_mov_b32_e32 v29, v161
	v_mov_b32_e32 v30, v161
	v_mov_b32_e32 v31, v161
	v_mov_b32_e32 v40, v161
	v_mov_b32_e32 v41, v161
	v_mov_b32_e32 v42, v161
	v_mov_b32_e32 v43, v161
	v_mov_b32_e32 v44, v161
	v_mov_b32_e32 v45, v161
	v_mov_b32_e32 v46, v161
	v_mov_b32_e32 v47, v161
	v_mov_b32_e32 v56, v161
	v_mov_b32_e32 v57, v161
	v_mov_b32_e32 v58, v161
	v_mov_b32_e32 v59, v161
	v_mov_b32_e32 v60, v161
	v_mov_b32_e32 v61, v161
	v_mov_b32_e32 v62, v161
	v_mov_b32_e32 v63, v161
	v_mov_b32_e32 v64, v161
	v_mov_b32_e32 v65, v161
	v_mov_b32_e32 v66, v161
	v_mov_b32_e32 v67, v161
	v_mov_b32_e32 v68, v161
	v_mov_b32_e32 v69, v161
	v_mov_b32_e32 v70, v161
	v_mov_b32_e32 v71, v161
	v_mov_b32_e32 v80, v161
	v_mov_b32_e32 v81, v161
	v_mov_b32_e32 v82, v161
	v_mov_b32_e32 v83, v161
	v_mov_b32_e32 v84, v161
	v_mov_b32_e32 v85, v161
	v_mov_b32_e32 v86, v161
	v_mov_b32_e32 v87, v161
	v_mov_b32_e32 v96, v161
	v_mov_b32_e32 v97, v161
	v_mov_b32_e32 v98, v161
	v_mov_b32_e32 v99, v161
	v_mov_b32_e32 v100, v161
	v_mov_b32_e32 v101, v161
	v_mov_b32_e32 v102, v161
	v_mov_b32_e32 v103, v161
	v_mov_b32_e32 v112, v161
	v_mov_b32_e32 v113, v161
	v_mov_b32_e32 v114, v161
	v_mov_b32_e32 v115, v161
	v_mov_b32_e32 v116, v161
	v_mov_b32_e32 v117, v161
	v_mov_b32_e32 v118, v161
	v_mov_b32_e32 v119, v161
	v_mov_b32_e32 v72, v161
	v_mov_b32_e32 v73, v161
	v_mov_b32_e32 v74, v161
	v_mov_b32_e32 v75, v161
	v_mov_b32_e32 v76, v161
	v_mov_b32_e32 v77, v161
	v_mov_b32_e32 v78, v161
	v_mov_b32_e32 v79, v161
	v_mov_b32_e32 v88, v161
	v_mov_b32_e32 v89, v161
	v_mov_b32_e32 v90, v161
	v_mov_b32_e32 v91, v161
	v_mov_b32_e32 v92, v161
	v_mov_b32_e32 v93, v161
	v_mov_b32_e32 v94, v161
	v_mov_b32_e32 v95, v161
	v_mov_b32_e32 v104, v161
	v_mov_b32_e32 v105, v161
	v_mov_b32_e32 v106, v161
	v_mov_b32_e32 v107, v161
	v_mov_b32_e32 v108, v161
	v_mov_b32_e32 v109, v161
	v_mov_b32_e32 v110, v161
	v_mov_b32_e32 v111, v161
	v_mov_b32_e32 v120, v161
	v_mov_b32_e32 v121, v161
	v_mov_b32_e32 v122, v161
	v_mov_b32_e32 v123, v161
	v_mov_b32_e32 v124, v161
	v_mov_b32_e32 v125, v161
	v_mov_b32_e32 v126, v161
	v_mov_b32_e32 v127, v161
	s_barrier
	s_branch .LBB0_349

.LBB0_938:
	s_mov_b64 s[18:19], 0x80
	s_add_i32 m0, s15, 0x18000
	v_lshl_add_u64 v[6:7], v[6:7], 0, s[18:19]
	s_waitcnt vmcnt(2)
	s_barrier
	global_load_lds_dwordx4 v[6:7], off
	v_lshl_add_u64 v[4:5], v[4:5], 0, s[18:19]
	s_add_i32 m0, s15, 0x1a000
	s_add_i32 s70, s15, 0x8000
	s_add_i32 s71, s15, 0xa000
	global_load_lds_dwordx4 v[4:5], off
	v_lshl_add_u64 v[0:1], v[0:1], 0, s[18:19]
	s_mov_b32 m0, s70
	s_add_u32 s8, s24, 0x80080
	global_load_lds_dwordx4 v[0:1], off
	v_lshl_add_u64 v[0:1], v[2:3], 0, s[18:19]
	s_mov_b32 m0, s71
	s_addc_u32 s9, s25, 0
	global_load_lds_dwordx4 v[0:1], off
	s_add_i32 m0, s15, 0x1c000
	v_lshl_add_u64 v[0:1], s[8:9], 0, v[178:179]
	global_load_lds_dwordx4 v[0:1], off
	v_lshl_add_u64 v[0:1], s[8:9], 0, v[182:183]
	s_add_i32 m0, s15, 0x1e000
	v_and_b32_e32 v192, 15, v189
	global_load_lds_dwordx4 v[0:1], off
	v_or_b32_e32 v0, s87, v192
	v_lshlrev_b32_e32 v1, 6, v0
	v_and_b32_e32 v1, 0x3c0, v1
	v_and_b32_e32 v191, 48, v189
	v_and_b32_e32 v3, 0xfffffc00, v190
	v_lshlrev_b32_e32 v0, 2, v0
	v_or_b32_e32 v2, v1, v191
	v_add_u32_e32 v4, s86, v3
	v_and_b32_e32 v0, 32, v0
	v_bitop3_b32 v4, v2, v4, v0 bitop3:0xde
	v_readlane_b32 s4, v250, 8
	v_lshlrev_b32_e32 v2, 2, v189
	v_bitop3_b32 v193, v1, v0, v191 bitop3:0x36
	v_lshl_or_b32 v0, v192, 6, v191
	v_add_u32_e32 v1, s4, v3
	v_and_b32_e32 v2, 32, v2
	v_bitop3_b32 v194, v0, v1, v2 bitop3:0xde
	v_and_b32_e32 v0, 0xffff0, v8
	v_add_u32_e32 v0, v9, v0
	v_lshl_add_u32 v170, v0, 12, v10
	v_and_b32_e32 v0, 0xffff0, v11
	s_waitcnt vmcnt(6)
	v_add_u32_e32 v0, v12, v0
	v_mov_b32_e32 v2, v169
	v_mov_b32_e32 v3, v169
	s_cmpk_lt_u32 s33, 0x100
	v_lshl_add_u32 v172, v0, 12, v13
	v_mov_b32_e32 v0, v169
	v_mov_b32_e32 v1, v169
	v_add_u32_e32 v195, 0, v4
	v_mov_b64_e32 v[6:7], v[2:3]
	v_mov_b64_e32 v[18:19], v[2:3]
	v_mov_b64_e32 v[22:23], v[2:3]
	v_mov_b64_e32 v[34:35], v[2:3]
	v_mov_b64_e32 v[38:39], v[2:3]
	v_mov_b64_e32 v[50:51], v[2:3]
	v_mov_b64_e32 v[54:55], v[2:3]
	v_mov_b64_e32 v[10:11], v[2:3]
	v_mov_b64_e32 v[14:15], v[2:3]
	v_mov_b64_e32 v[26:27], v[2:3]
	v_mov_b64_e32 v[30:31], v[2:3]
	v_mov_b64_e32 v[42:43], v[2:3]
	v_mov_b64_e32 v[46:47], v[2:3]
	v_mov_b64_e32 v[58:59], v[2:3]
	v_mov_b64_e32 v[62:63], v[2:3]
	v_mov_b64_e32 v[66:67], v[2:3]
	v_mov_b64_e32 v[70:71], v[2:3]
	v_mov_b64_e32 v[82:83], v[2:3]
	v_mov_b64_e32 v[86:87], v[2:3]
	v_mov_b64_e32 v[98:99], v[2:3]
	v_mov_b64_e32 v[102:103], v[2:3]
	v_mov_b64_e32 v[118:119], v[2:3]
	v_mov_b64_e32 v[122:123], v[2:3]
	v_mov_b64_e32 v[74:75], v[2:3]
	v_mov_b64_e32 v[78:79], v[2:3]
	v_mov_b64_e32 v[90:91], v[2:3]
	v_mov_b64_e32 v[94:95], v[2:3]
	v_mov_b64_e32 v[110:111], v[2:3]
	v_mov_b64_e32 v[114:115], v[2:3]
	v_mov_b64_e32 v[130:131], v[2:3]
	v_mov_b64_e32 v[134:135], v[2:3]
	s_sext_i32_i8 s72, s6
	s_mov_b64 s[20:21], 0x80080
	s_cselect_b64 s[22:23], -1, 0
	v_mov_b32_e32 v171, v169
	v_mov_b32_e32 v173, v169
	s_mov_b32 s62, 0
	v_mov_b64_e32 v[174:175], 0x100
	v_mov_b64_e32 v[176:177], 0xff
	v_mov_b64_e32 v[4:5], v[0:1]
	v_mov_b64_e32 v[16:17], v[0:1]
	v_mov_b64_e32 v[20:21], v[0:1]
	v_mov_b64_e32 v[32:33], v[0:1]
	v_mov_b64_e32 v[36:37], v[0:1]
	v_mov_b64_e32 v[48:49], v[0:1]
	v_mov_b64_e32 v[52:53], v[0:1]
	v_mov_b64_e32 v[8:9], v[0:1]
	v_mov_b64_e32 v[12:13], v[0:1]
	v_mov_b64_e32 v[24:25], v[0:1]
	v_mov_b64_e32 v[28:29], v[0:1]
	v_mov_b64_e32 v[40:41], v[0:1]
	v_mov_b64_e32 v[44:45], v[0:1]
	v_mov_b64_e32 v[56:57], v[0:1]
	v_mov_b64_e32 v[60:61], v[0:1]
	v_mov_b64_e32 v[64:65], v[0:1]
	v_mov_b64_e32 v[68:69], v[0:1]
	v_mov_b64_e32 v[80:81], v[0:1]
	v_mov_b64_e32 v[84:85], v[0:1]
	v_mov_b64_e32 v[96:97], v[0:1]
	v_mov_b64_e32 v[100:101], v[0:1]
	v_mov_b64_e32 v[116:117], v[0:1]
	v_mov_b64_e32 v[120:121], v[0:1]
	v_mov_b64_e32 v[72:73], v[0:1]
	v_mov_b64_e32 v[76:77], v[0:1]
	v_mov_b64_e32 v[88:89], v[0:1]
	v_mov_b64_e32 v[92:93], v[0:1]
	v_mov_b64_e32 v[108:109], v[0:1]
	v_mov_b64_e32 v[112:113], v[0:1]
	v_mov_b64_e32 v[128:129], v[0:1]
	v_mov_b64_e32 v[132:133], v[0:1]
	s_barrier
	s_branch .LBB0_941

.LBB0_987:
	s_mov_b64 s[14:15], 0x80
	s_add_i32 m0, s90, 0x18000
	v_lshl_add_u64 v[6:7], v[6:7], 0, s[14:15]
	s_waitcnt vmcnt(2)
	s_barrier
	global_load_lds_dwordx4 v[6:7], off
	v_lshl_add_u64 v[4:5], v[4:5], 0, s[14:15]
	s_add_i32 m0, s90, 0x1a000
	s_add_i32 s75, s90, 0x8000
	s_add_i32 s76, s90, 0xa000
	global_load_lds_dwordx4 v[4:5], off
	v_lshl_add_u64 v[0:1], v[0:1], 0, s[14:15]
	s_mov_b32 m0, s75
	s_add_u32 s16, s28, 0x10080
	global_load_lds_dwordx4 v[0:1], off
	v_lshl_add_u64 v[0:1], v[2:3], 0, s[14:15]
	s_mov_b32 m0, s76
	s_addc_u32 s17, s29, 0
	global_load_lds_dwordx4 v[0:1], off
	s_add_i32 m0, s90, 0x1c000
	v_lshl_add_u64 v[0:1], s[16:17], 0, v[130:131]
	global_load_lds_dwordx4 v[0:1], off
	v_lshl_add_u64 v[0:1], s[16:17], 0, v[134:135]
	s_add_i32 m0, s90, 0x1e000
	s_sext_i32_i8 s81, s6
	global_load_lds_dwordx4 v[0:1], off
	v_and_b32_e32 v0, 15, v8
	v_or_b32_e32 v140, s87, v0
	v_lshlrev_b32_e32 v3, 6, v140
	v_and_b32_e32 v4, 48, v8
	s_movk_i32 s6, 0x3c0
	v_ashrrev_i32_e32 v2, 6, v8
	v_and_or_b32 v3, v3, s6, v4
	v_lshlrev_b32_e32 v6, 2, v140
	v_lshl_or_b32 v0, v0, 6, v4
	v_readlane_b32 s6, v250, 2
	v_lshlrev_b32_e32 v4, 2, v8
	v_ashrrev_i32_e32 v1, 1, v8
	v_lshl_add_u32 v5, v2, 10, s86
	v_and_b32_e32 v6, 32, v6
	v_add_lshl_u32 v2, v2, s6, 10
	v_and_b32_e32 v4, 32, v4
	s_waitcnt vmcnt(6)
	s_cmpk_lt_u32 s33, 0x100
	v_and_b32_e32 v1, -8, v1
	v_bitop3_b32 v3, v3, v5, v6 bitop3:0xde
	v_bitop3_b32 v141, v0, v2, v4 bitop3:0xde
	s_cselect_b64 s[16:17], -1, 0
	v_readlane_b32 s6, v250, 1
	s_add_i32 s79, 0, 0x10000
	s_add_i32 s80, 0, 0x14000
	v_add_u32_e32 v142, s6, v1
	s_ashr_i32 s77, s46, 31
	s_mov_b32 s78, s46
	v_mov_b64_e32 v[136:137], 0x100
	v_mov_b64_e32 v[138:139], 0xff
	v_add_u32_e32 v143, s79, v141
	v_add_u32_e32 v144, s80, v141
	v_add_u32_e32 v145, 0, v3
	s_barrier
	s_branch .LBB0_990

.LBB0_1243:
	s_mov_b64 s[16:17], 0x80
	s_add_i32 m0, s40, 0x18000
	v_lshl_add_u64 v[6:7], v[6:7], 0, s[16:17]
	s_waitcnt vmcnt(2)
	s_barrier
	global_load_lds_dwordx4 v[6:7], off
	v_lshl_add_u64 v[4:5], v[4:5], 0, s[16:17]
	s_add_i32 m0, s40, 0x1a000
	s_add_i32 s65, s40, 0x8000
	s_add_i32 s66, s40, 0xa000
	s_sext_i32_i8 s64, s6
	global_load_lds_dwordx4 v[4:5], off
	v_lshl_add_u64 v[0:1], v[0:1], 0, s[16:17]
	s_mov_b32 m0, s65
	s_add_u32 s6, s28, 0xb0080
	global_load_lds_dwordx4 v[0:1], off
	v_lshl_add_u64 v[0:1], v[2:3], 0, s[16:17]
	s_mov_b32 m0, s66
	s_addc_u32 s7, s29, 0
	global_load_lds_dwordx4 v[0:1], off
	s_add_i32 m0, s40, 0x1c000
	v_lshl_add_u64 v[0:1], s[6:7], 0, v[170:171]
	global_load_lds_dwordx4 v[0:1], off
	v_lshl_add_u64 v[0:1], s[6:7], 0, v[174:175]
	s_add_i32 m0, s40, 0x1e000
	v_and_b32_e32 v189, 15, v186
	global_load_lds_dwordx4 v[0:1], off
	v_or_b32_e32 v14, s87, v189
	v_lshlrev_b32_e32 v15, 6, v14
	v_and_b32_e32 v15, 0x3c0, v15
	v_and_b32_e32 v188, 48, v186
	v_and_b32_e32 v17, 0xfffffc00, v187
	v_lshlrev_b32_e32 v14, 2, v14
	v_and_b32_e32 v0, 0xffff0, v8
	v_or_b32_e32 v16, v15, v188
	v_add_u32_e32 v18, s86, v17
	v_and_b32_e32 v14, 32, v14
	v_readlane_b32 s4, v250, 8
	v_add_lshl_u32 v0, v9, v0, 12
	v_bitop3_b32 v191, v15, v14, v188 bitop3:0x36
	v_bitop3_b32 v14, v16, v18, v14 bitop3:0xde
	v_add_u32_e32 v16, s4, v17
	v_lshlrev_b32_e32 v17, 2, v186
	s_waitcnt vmcnt(6)
	v_lshl_add_u32 v162, v10, 1, v0
	v_and_b32_e32 v0, 0xffff0, v11
	v_lshl_or_b32 v15, v189, 6, v188
	v_and_b32_e32 v17, 32, v17
	s_cmpk_lt_u32 s33, 0x100
	v_add_lshl_u32 v0, v12, v0, 12
	v_bitop3_b32 v192, v15, v16, v17 bitop3:0xde
	s_cselect_b64 s[18:19], -1, 0
	v_lshl_add_u32 v164, v13, 1, v0
	v_mov_b32_e32 v163, v161
	v_mov_b32_e32 v165, v161
	v_mov_b64_e32 v[166:167], 0x100
	v_mov_b64_e32 v[168:169], 0xff
	v_add_u32_e32 v193, 0, v14
	v_mov_b32_e32 v32, v161
	v_mov_b32_e32 v33, v161
	v_mov_b32_e32 v34, v161
	v_mov_b32_e32 v35, v161
	v_mov_b32_e32 v36, v161
	v_mov_b32_e32 v37, v161
	v_mov_b32_e32 v38, v161
	v_mov_b32_e32 v39, v161
	v_mov_b32_e32 v48, v161
	v_mov_b32_e32 v49, v161
	v_mov_b32_e32 v50, v161
	v_mov_b32_e32 v51, v161
	v_mov_b32_e32 v52, v161
	v_mov_b32_e32 v53, v161
	v_mov_b32_e32 v54, v161
	v_mov_b32_e32 v55, v161
	v_mov_b32_e32 v64, v161
	v_mov_b32_e32 v65, v161
	v_mov_b32_e32 v66, v161
	v_mov_b32_e32 v67, v161
	v_mov_b32_e32 v68, v161
	v_mov_b32_e32 v69, v161
	v_mov_b32_e32 v70, v161
	v_mov_b32_e32 v71, v161
	v_mov_b32_e32 v80, v161
	v_mov_b32_e32 v81, v161
	v_mov_b32_e32 v82, v161
	v_mov_b32_e32 v83, v161
	v_mov_b32_e32 v84, v161
	v_mov_b32_e32 v85, v161
	v_mov_b32_e32 v86, v161
	v_mov_b32_e32 v87, v161
	v_mov_b32_e32 v40, v161
	v_mov_b32_e32 v41, v161
	v_mov_b32_e32 v42, v161
	v_mov_b32_e32 v43, v161
	v_mov_b32_e32 v44, v161
	v_mov_b32_e32 v45, v161
	v_mov_b32_e32 v46, v161
	v_mov_b32_e32 v47, v161
	v_mov_b32_e32 v56, v161
	v_mov_b32_e32 v57, v161
	v_mov_b32_e32 v58, v161
	v_mov_b32_e32 v59, v161
	v_mov_b32_e32 v60, v161
	v_mov_b32_e32 v61, v161
	v_mov_b32_e32 v62, v161
	v_mov_b32_e32 v63, v161
	v_mov_b32_e32 v72, v161
	v_mov_b32_e32 v73, v161
	v_mov_b32_e32 v74, v161
	v_mov_b32_e32 v75, v161
	v_mov_b32_e32 v76, v161
	v_mov_b32_e32 v77, v161
	v_mov_b32_e32 v78, v161
	v_mov_b32_e32 v79, v161
	v_mov_b32_e32 v88, v161
	v_mov_b32_e32 v89, v161
	v_mov_b32_e32 v90, v161
	v_mov_b32_e32 v91, v161
	v_mov_b32_e32 v92, v161
	v_mov_b32_e32 v93, v161
	v_mov_b32_e32 v94, v161
	v_mov_b32_e32 v95, v161
	v_mov_b32_e32 v96, v161
	v_mov_b32_e32 v97, v161
	v_mov_b32_e32 v98, v161
	v_mov_b32_e32 v99, v161
	v_mov_b32_e32 v100, v161
	v_mov_b32_e32 v101, v161
	v_mov_b32_e32 v102, v161
	v_mov_b32_e32 v103, v161
	v_mov_b32_e32 v112, v161
	v_mov_b32_e32 v113, v161
	v_mov_b32_e32 v114, v161
	v_mov_b32_e32 v115, v161
	v_mov_b32_e32 v116, v161
	v_mov_b32_e32 v117, v161
	v_mov_b32_e32 v118, v161
	v_mov_b32_e32 v119, v161
	v_mov_b32_e32 v128, v161
	v_mov_b32_e32 v129, v161
	v_mov_b32_e32 v130, v161
	v_mov_b32_e32 v131, v161
	v_mov_b32_e32 v132, v161
	v_mov_b32_e32 v133, v161
	v_mov_b32_e32 v134, v161
	v_mov_b32_e32 v135, v161
	v_mov_b32_e32 v144, v161
	v_mov_b32_e32 v145, v161
	v_mov_b32_e32 v146, v161
	v_mov_b32_e32 v147, v161
	v_mov_b32_e32 v148, v161
	v_mov_b32_e32 v149, v161
	v_mov_b32_e32 v150, v161
	v_mov_b32_e32 v151, v161
	v_mov_b32_e32 v104, v161
	v_mov_b32_e32 v105, v161
	v_mov_b32_e32 v106, v161
	v_mov_b32_e32 v107, v161
	v_mov_b32_e32 v108, v161
	v_mov_b32_e32 v109, v161
	v_mov_b32_e32 v110, v161
	v_mov_b32_e32 v111, v161
	v_mov_b32_e32 v120, v161
	v_mov_b32_e32 v121, v161
	v_mov_b32_e32 v122, v161
	v_mov_b32_e32 v123, v161
	v_mov_b32_e32 v124, v161
	v_mov_b32_e32 v125, v161
	v_mov_b32_e32 v126, v161
	v_mov_b32_e32 v127, v161
	v_mov_b32_e32 v136, v161
	v_mov_b32_e32 v137, v161
	v_mov_b32_e32 v138, v161
	v_mov_b32_e32 v139, v161
	v_mov_b32_e32 v140, v161
	v_mov_b32_e32 v141, v161
	v_mov_b32_e32 v142, v161
	v_mov_b32_e32 v143, v161
	v_mov_b32_e32 v152, v161
	v_mov_b32_e32 v153, v161
	v_mov_b32_e32 v154, v161
	v_mov_b32_e32 v155, v161
	v_mov_b32_e32 v156, v161
	v_mov_b32_e32 v157, v161
	v_mov_b32_e32 v158, v161
	v_mov_b32_e32 v159, v161
	s_barrier
	s_branch .LBB0_1246
